# grid barrier: acquire-side buffer_inv sc1 issued at arrival, after the arrival atomic has returned (no reliance on vmcnt completion order); post-release invalidates dropped
# speedup vs baseline: 1.0018x; 1.0018x over previous
.LBB0_25:
	s_or_b64 exec, exec, s[10:11]
	v_cvt_f32_u32_e32 v5, v3
	s_waitcnt vmcnt(0)
	v_readfirstlane_b32 s8, v4
	buffer_inv sc1
	v_sub_u32_e32 v4, 0, v3
	v_rcp_iflag_f32_e32 v5, v5
	v_add_u32_e32 v6, s8, v2
	v_mul_f32_e32 v5, 0x4f7ffffe, v5
	v_cvt_u32_f32_e32 v5, v5
	v_mul_lo_u32 v2, v4, v5
	v_mul_hi_u32 v2, v5, v2
	v_add_u32_e32 v2, v5, v2
	v_mul_hi_u32 v2, v6, v2
	v_mul_lo_u32 v4, v2, v3
	v_sub_u32_e32 v4, v6, v4
	v_add_u32_e32 v5, 1, v2
	v_cmp_ge_u32_e32 vcc, v4, v3
	s_nop 1
	v_cndmask_b32_e32 v2, v2, v5, vcc
	v_sub_u32_e32 v5, v4, v3
	v_cndmask_b32_e32 v4, v4, v5, vcc
	v_add_u32_e32 v5, 1, v2
	v_cmp_ge_u32_e32 vcc, v4, v3
	v_add_u32_e32 v4, 1, v6
	s_nop 0
	v_cndmask_b32_e32 v2, v2, v5, vcc
	v_mul_lo_u32 v5, v3, v2
	v_add_u32_e32 v3, v5, v3
	v_cmp_ne_u32_e32 vcc, v4, v3
	s_and_saveexec_b64 s[8:9], vcc
	s_xor_b64 s[8:9], exec, s[8:9]
	s_cbranch_execz .LBB0_39
	s_waitcnt lgkmcnt(0)
	v_mov_b32_e32 v1, 0x2000
	global_load_dword v1, v1, s[2:3] offset:1024 sc1
	s_add_u32 s14, s2, 0x2400
	s_addc_u32 s15, s3, 0
	s_waitcnt vmcnt(0)
	v_cmp_eq_u32_e32 vcc, v1, v2
	s_and_saveexec_b64 s[10:11], vcc
	s_cbranch_execz .LBB0_38
	s_add_u32 s12, s62, 0x1e800600
	s_addc_u32 s13, s63, 0
	s_mov_b32 s26, 1
	s_mov_b64 s[16:17], 0
	v_mov_b32_e32 v1, 0
	s_branch .LBB0_29

.LBB0_144:
	s_or_b64 exec, exec, s[12:13]
	v_cvt_f32_u32_e32 v5, v3
	s_waitcnt vmcnt(0)
	v_readfirstlane_b32 s10, v4
	buffer_inv sc1
	s_add_u32 s8, s8, 0x2400
	s_addc_u32 s9, s9, 0
	v_rcp_iflag_f32_e32 v5, v5
	v_add_u32_e32 v6, s10, v2
	v_mul_f32_e32 v4, 0x4f7ffffe, v5
	v_cvt_u32_f32_e32 v4, v4
	v_sub_u32_e32 v5, 0, v3
	v_mul_lo_u32 v2, v5, v4
	v_mul_hi_u32 v2, v4, v2
	v_add_u32_e32 v2, v4, v2
	v_mul_hi_u32 v2, v6, v2
	v_mul_lo_u32 v4, v2, v3
	v_sub_u32_e32 v4, v6, v4
	v_add_u32_e32 v5, 1, v2
	v_cmp_ge_u32_e32 vcc, v4, v3
	s_nop 1
	v_cndmask_b32_e32 v2, v2, v5, vcc
	v_sub_u32_e32 v5, v4, v3
	v_cndmask_b32_e32 v4, v4, v5, vcc
	v_add_u32_e32 v5, 1, v2
	v_cmp_ge_u32_e32 vcc, v4, v3
	v_add_u32_e32 v4, 1, v6
	s_nop 0
	v_cndmask_b32_e32 v2, v2, v5, vcc
	v_mul_lo_u32 v5, v3, v2
	v_add_u32_e32 v3, v5, v3
	v_cmp_ne_u32_e32 vcc, v4, v3
	s_and_saveexec_b64 s[10:11], vcc
	s_xor_b64 s[10:11], exec, s[10:11]
	s_cbranch_execz .LBB0_158
	s_waitcnt lgkmcnt(0)
	v_mov_b32_e32 v1, 0
	global_load_dword v3, v1, s[8:9] sc1
	s_waitcnt vmcnt(0)
	v_cmp_eq_u32_e32 vcc, v3, v2
	s_and_saveexec_b64 s[12:13], vcc
	s_cbranch_execz .LBB0_157
	s_mov_b32 s24, 1
	s_mov_b64 s[14:15], 0
	s_branch .LBB0_148

.LBB0_396:
	s_or_b64 exec, exec, s[10:11]
	v_cvt_f32_u32_e32 v5, v3
	s_waitcnt vmcnt(0)
	v_readfirstlane_b32 s8, v4
	buffer_inv sc1
	s_add_u32 s4, s4, 0x2400
	s_addc_u32 s5, s5, 0
	v_rcp_iflag_f32_e32 v5, v5
	v_add_u32_e32 v6, s8, v2
	v_mul_f32_e32 v4, 0x4f7ffffe, v5
	v_cvt_u32_f32_e32 v4, v4
	v_sub_u32_e32 v5, 0, v3
	v_mul_lo_u32 v2, v5, v4
	v_mul_hi_u32 v2, v4, v2
	v_add_u32_e32 v2, v4, v2
	v_mul_hi_u32 v2, v6, v2
	v_mul_lo_u32 v4, v2, v3
	v_sub_u32_e32 v4, v6, v4
	v_add_u32_e32 v5, 1, v2
	v_cmp_ge_u32_e32 vcc, v4, v3
	s_nop 1
	v_cndmask_b32_e32 v2, v2, v5, vcc
	v_sub_u32_e32 v5, v4, v3
	v_cndmask_b32_e32 v4, v4, v5, vcc
	v_add_u32_e32 v5, 1, v2
	v_cmp_ge_u32_e32 vcc, v4, v3
	v_add_u32_e32 v4, 1, v6
	s_nop 0
	v_cndmask_b32_e32 v2, v2, v5, vcc
	v_mul_lo_u32 v5, v3, v2
	v_add_u32_e32 v3, v5, v3
	v_cmp_ne_u32_e32 vcc, v4, v3
	s_and_saveexec_b64 s[8:9], vcc
	s_xor_b64 s[8:9], exec, s[8:9]
	s_cbranch_execz .LBB0_410
	s_waitcnt lgkmcnt(0)
	v_mov_b32_e32 v1, 0
	global_load_dword v3, v1, s[4:5] sc1
	s_waitcnt vmcnt(0)
	v_cmp_eq_u32_e32 vcc, v3, v2
	s_and_saveexec_b64 s[10:11], vcc
	s_cbranch_execz .LBB0_409
	s_mov_b32 s22, 1
	s_mov_b64 s[12:13], 0
	s_branch .LBB0_400

.LBB0_534:
	s_or_b64 exec, exec, s[6:7]
	v_cvt_f32_u32_e32 v5, v3
	s_waitcnt vmcnt(0)
	v_readfirstlane_b32 s4, v4
	buffer_inv sc1
	v_sub_u32_e32 v4, 0, v3
	v_rcp_iflag_f32_e32 v5, v5
	v_add_u32_e32 v6, s4, v2
	v_mul_f32_e32 v5, 0x4f7ffffe, v5
	v_cvt_u32_f32_e32 v5, v5
	v_mul_lo_u32 v2, v4, v5
	v_mul_hi_u32 v2, v5, v2
	v_add_u32_e32 v2, v5, v2
	v_mul_hi_u32 v2, v6, v2
	v_mul_lo_u32 v4, v2, v3
	v_sub_u32_e32 v4, v6, v4
	v_add_u32_e32 v5, 1, v2
	v_cmp_ge_u32_e32 vcc, v4, v3
	s_nop 1
	v_cndmask_b32_e32 v2, v2, v5, vcc
	v_sub_u32_e32 v5, v4, v3
	v_cndmask_b32_e32 v4, v4, v5, vcc
	v_add_u32_e32 v5, 1, v2
	v_cmp_ge_u32_e32 vcc, v4, v3
	v_add_u32_e32 v4, 1, v6
	s_nop 0
	v_cndmask_b32_e32 v2, v2, v5, vcc
	v_mul_lo_u32 v5, v3, v2
	v_add_u32_e32 v3, v5, v3
	v_cmp_ne_u32_e32 vcc, v4, v3
	s_and_saveexec_b64 s[4:5], vcc
	s_xor_b64 s[4:5], exec, s[4:5]
	s_cbranch_execz .LBB0_548
	s_waitcnt lgkmcnt(0)
	v_mov_b32_e32 v1, 0x2000
	global_load_dword v1, v1, s[2:3] offset:1024 sc1
	s_add_u32 s10, s2, 0x2400
	s_addc_u32 s11, s3, 0
	s_waitcnt vmcnt(0)
	v_cmp_eq_u32_e32 vcc, v1, v2
	s_and_saveexec_b64 s[6:7], vcc
	s_cbranch_execz .LBB0_547
	s_add_u32 s8, s62, 0x1e800600
	s_addc_u32 s9, s63, 0
	s_mov_b32 s22, 1
	s_mov_b64 s[12:13], 0
	v_mov_b32_e32 v1, 0
	s_branch .LBB0_538

.LBB0_681:
	s_or_b64 exec, exec, s[8:9]
	v_cvt_f32_u32_e32 v5, v3
	s_waitcnt vmcnt(0)
	v_readfirstlane_b32 s6, v4
	buffer_inv sc1
	v_sub_u32_e32 v4, 0, v3
	v_rcp_iflag_f32_e32 v5, v5
	v_add_u32_e32 v6, s6, v2
	v_mul_f32_e32 v5, 0x4f7ffffe, v5
	v_cvt_u32_f32_e32 v5, v5
	v_mul_lo_u32 v2, v4, v5
	v_mul_hi_u32 v2, v5, v2
	v_add_u32_e32 v2, v5, v2
	v_mul_hi_u32 v2, v6, v2
	v_mul_lo_u32 v4, v2, v3
	v_sub_u32_e32 v4, v6, v4
	v_add_u32_e32 v5, 1, v2
	v_cmp_ge_u32_e32 vcc, v4, v3
	s_nop 1
	v_cndmask_b32_e32 v2, v2, v5, vcc
	v_sub_u32_e32 v5, v4, v3
	v_cndmask_b32_e32 v4, v4, v5, vcc
	v_add_u32_e32 v5, 1, v2
	v_cmp_ge_u32_e32 vcc, v4, v3
	v_add_u32_e32 v4, 1, v6
	s_nop 0
	v_cndmask_b32_e32 v2, v2, v5, vcc
	v_mul_lo_u32 v5, v3, v2
	v_add_u32_e32 v3, v5, v3
	v_cmp_ne_u32_e32 vcc, v4, v3
	s_and_saveexec_b64 s[6:7], vcc
	s_xor_b64 s[6:7], exec, s[6:7]
	s_cbranch_execz .LBB0_695
	s_waitcnt lgkmcnt(0)
	v_mov_b32_e32 v1, 0x2000
	global_load_dword v1, v1, s[4:5] offset:1024 sc1
	s_add_u32 s12, s4, 0x2400
	s_addc_u32 s13, s5, 0
	s_waitcnt vmcnt(0)
	v_cmp_eq_u32_e32 vcc, v1, v2
	s_and_saveexec_b64 s[8:9], vcc
	s_cbranch_execz .LBB0_694
	s_add_u32 s10, s62, 0x1e800600
	s_addc_u32 s11, s63, 0
	s_mov_b32 s24, 1
	s_mov_b64 s[14:15], 0
	v_mov_b32_e32 v1, 0
	s_branch .LBB0_685

.LBB0_776:
	s_or_b64 exec, exec, s[8:9]
	v_cvt_f32_u32_e32 v5, v3
	s_waitcnt vmcnt(0)
	v_readfirstlane_b32 s4, v4
	buffer_inv sc1
	v_sub_u32_e32 v4, 0, v3
	v_rcp_iflag_f32_e32 v5, v5
	v_add_u32_e32 v6, s4, v2
	v_mul_f32_e32 v5, 0x4f7ffffe, v5
	v_cvt_u32_f32_e32 v5, v5
	v_mul_lo_u32 v2, v4, v5
	v_mul_hi_u32 v2, v5, v2
	v_add_u32_e32 v2, v5, v2
	v_mul_hi_u32 v2, v6, v2
	v_mul_lo_u32 v4, v2, v3
	v_sub_u32_e32 v4, v6, v4
	v_add_u32_e32 v5, 1, v2
	v_cmp_ge_u32_e32 vcc, v4, v3
	s_nop 1
	v_cndmask_b32_e32 v2, v2, v5, vcc
	v_sub_u32_e32 v5, v4, v3
	v_cndmask_b32_e32 v4, v4, v5, vcc
	v_add_u32_e32 v5, 1, v2
	v_cmp_ge_u32_e32 vcc, v4, v3
	v_add_u32_e32 v4, 1, v6
	s_nop 0
	v_cndmask_b32_e32 v2, v2, v5, vcc
	v_mul_lo_u32 v5, v3, v2
	v_add_u32_e32 v3, v5, v3
	v_cmp_ne_u32_e32 vcc, v4, v3
	s_and_saveexec_b64 s[4:5], vcc
	s_xor_b64 s[4:5], exec, s[4:5]
	s_cbranch_execz .LBB0_790
	s_waitcnt lgkmcnt(0)
	v_mov_b32_e32 v1, 0x2000
	global_load_dword v1, v1, s[2:3] offset:1024 sc1
	s_add_u32 s12, s2, 0x2400
	s_addc_u32 s13, s3, 0
	s_waitcnt vmcnt(0)
	v_cmp_eq_u32_e32 vcc, v1, v2
	s_and_saveexec_b64 s[8:9], vcc
	s_cbranch_execz .LBB0_789
	s_add_u32 s10, s62, 0x1e800600
	s_addc_u32 s11, s63, 0
	s_mov_b32 s24, 1
	s_mov_b64 s[14:15], 0
	v_mov_b32_e32 v1, 0
	s_branch .LBB0_780
